# attention loop: leftover pads, redundant vmcnt waits and add-zero removed (exact, 40 bytes)
# speedup vs baseline: 1.0013x; 1.0013x over previous
.LBB0_215:
	v_lshl_add_u64 v[150:151], v[148:149], 0, s[58:59]
	ds_read_b128 v[64:67], v181 offset:49152
	ds_read_b128 v[68:71], v181 offset:57344
	v_add_f32_e32 v128, v235, v234
	v_add_f32_e32 v128, v236, v128
	s_waitcnt lgkmcnt(1)
	v_mfma_f32_32x32x16_bf16 v[80:95], v[64:67], v[108:111], 0
	v_add_f32_e32 v128, v237, v128
	v_add_f32_e32 v128, v238, v128
	ds_read_b128 v[202:205], v182 offset:49152
	ds_read_b128 v[206:209], v182 offset:57344
	v_add_f32_e32 v128, v239, v128
	v_add_f32_e32 v128, v240, v128
	v_add_f32_e32 v128, v241, v128
	v_add_f32_e32 v128, v242, v128
	s_waitcnt lgkmcnt(2)
	v_mfma_f32_32x32x16_bf16 v[64:79], v[68:71], v[108:111], 0
	v_add_f32_e32 v128, v243, v128
	v_add_f32_e32 v128, v244, v128
	v_add_f32_e32 v128, v245, v128
	v_add_f32_e32 v128, v246, v128
	v_add_f32_e32 v128, v247, v128
	v_add_f32_e32 v128, v252, v128
	v_add_f32_e32 v128, v253, v128
	s_waitcnt lgkmcnt(1)
	v_mfma_f32_32x32x16_bf16 v[80:95], v[202:205], v[104:107], v[80:95]
	v_add_f32_e32 v128, v218, v128
	v_add_f32_e32 v128, v219, v128
	v_add_f32_e32 v128, v220, v128
	v_add_f32_e32 v128, v221, v128
	v_add_f32_e32 v128, v222, v128
	v_add_f32_e32 v128, v223, v128
	v_add_f32_e32 v128, v224, v128
	s_waitcnt lgkmcnt(0)
	v_mfma_f32_32x32x16_bf16 v[64:79], v[206:209], v[104:107], v[64:79]
	ds_read_b128 v[202:205], v183 offset:49152
	ds_read_b128 v[206:209], v183 offset:57344
	v_add_f32_e32 v128, v225, v128
	v_add_f32_e32 v128, v226, v128
	v_add_f32_e32 v128, v227, v128
	v_add_f32_e32 v128, v228, v128
	v_add_f32_e32 v128, v229, v128
	v_add_f32_e32 v128, v230, v128
	s_waitcnt lgkmcnt(1)
	v_mfma_f32_32x32x16_bf16 v[80:95], v[202:205], v[100:103], v[80:95]
	v_add_f32_e32 v128, v231, v128
	v_add_f32_e32 v128, v232, v128
	v_add_f32_e32 v187, v233, v128
	v_mov_b32_e32 v188, v187
	v_lshl_add_u64 v[152:153], v[146:147], 0, s[58:59]
	s_nop 0
	v_permlane32_swap_b32_e32 v187, v188
	s_waitcnt lgkmcnt(0)
	v_mfma_f32_32x32x16_bf16 v[64:79], v[206:209], v[100:103], v[64:79]
	ds_read_b128 v[202:205], v184 offset:49152
	ds_read_b128 v[206:209], v184 offset:57344
	v_cvt_pk_bf16_f32 v128, v234, v235
	v_cvt_pk_bf16_f32 v129, v236, v237
	v_cvt_pk_bf16_f32 v130, v238, v239
	v_cvt_pk_bf16_f32 v131, v240, v241
	v_cvt_pk_bf16_f32 v198, v242, v243
	v_cvt_pk_bf16_f32 v199, v244, v245
	s_waitcnt lgkmcnt(1)
	v_mfma_f32_32x32x16_bf16 v[80:95], v[202:205], v[96:99], v[80:95]
	v_permlane32_swap_b32_e32 v128, v130
	v_cvt_pk_bf16_f32 v200, v246, v247
	v_cvt_pk_bf16_f32 v201, v252, v253
	v_cvt_pk_bf16_f32 v190, v218, v219
	v_cvt_pk_bf16_f32 v191, v220, v221
	v_cvt_pk_bf16_f32 v192, v222, v223
	s_waitcnt lgkmcnt(0)
	v_mfma_f32_32x32x16_bf16 v[64:79], v[206:209], v[96:99], v[64:79]
	v_add_co_u32_e32 v116, vcc, s86, v152
	s_nop 1
	v_addc_co_u32_e32 v117, vcc, 0, v153, vcc
	v_add_co_u32_e32 v120, vcc, s86, v150
	s_nop 1
	v_addc_co_u32_e32 v121, vcc, 0, v151, vcc
	ds_read_b64_tr_b16 v[202:203], v177 offset:0
	ds_read_b64_tr_b16 v[204:205], v177 offset:0x800
	ds_read_b64_tr_b16 v[206:207], v177 offset:0x1000
	ds_read_b64_tr_b16 v[208:209], v177 offset:0x1800
	ds_read_b64_tr_b16 v[210:211], v177 offset:0x2000
	ds_read_b64_tr_b16 v[212:213], v177 offset:0x2800
	ds_read_b64_tr_b16 v[214:215], v177 offset:0x3000
	ds_read_b64_tr_b16 v[216:217], v177 offset:0x3800
	v_cvt_pk_bf16_f32 v193, v224, v225
	v_cvt_pk_bf16_f32 v194, v226, v227
	v_cvt_pk_bf16_f32 v195, v228, v229
	v_cvt_pk_bf16_f32 v196, v230, v231
	v_cvt_pk_bf16_f32 v197, v232, v233
	v_permlane32_swap_b32_e32 v129, v131
	v_permlane32_swap_b32_e32 v198, v200
	v_permlane32_swap_b32_e32 v199, v201
	v_permlane32_swap_b32_e32 v190, v192
	v_permlane32_swap_b32_e32 v191, v193
	v_permlane32_swap_b32_e32 v194, v196
	v_permlane32_swap_b32_e32 v195, v197
	global_load_dwordx4 v[112:115], v[116:117], off offset:1024
	s_nop 0
	global_load_dwordx4 v[116:119], v[116:117], off
	s_nop 0
	global_load_dwordx4 v[124:127], v[120:121], off offset:1024
	s_nop 0
	global_load_dwordx4 v[120:123], v[120:121], off
	s_waitcnt lgkmcnt(6)
	v_mfma_f32_32x32x16_bf16 v[0:15], v[128:131], v[202:205], v[0:15]
	ds_read_b64_tr_b16 v[202:203], v177 offset:0x200
	ds_read_b64_tr_b16 v[204:205], v177 offset:0xa00
	v_max_f32_e32 v250, v80, v81
	v_max3_f32 v250, v250, v82, v83
	v_max3_f32 v250, v250, v84, v85
	v_max3_f32 v250, v250, v86, v87
	v_max3_f32 v250, v250, v88, v89
	v_max3_f32 v250, v250, v90, v91
	v_max3_f32 v250, v250, v92, v93
	s_waitcnt lgkmcnt(6)
	v_mfma_f32_32x32x16_bf16 v[0:15], v[198:201], v[206:209], v[0:15]
	ds_read_b64_tr_b16 v[206:207], v177 offset:0x1200
	ds_read_b64_tr_b16 v[208:209], v177 offset:0x1a00
	v_max3_f32 v250, v250, v94, v95
	v_max3_f32 v250, v250, v64, v65
	v_max3_f32 v250, v250, v66, v67
	v_max3_f32 v250, v250, v68, v69
	v_max3_f32 v250, v250, v70, v71
	v_max3_f32 v250, v250, v72, v73
	v_max3_f32 v250, v250, v74, v75
	v_max3_f32 v250, v250, v76, v77
	v_max3_f32 v250, v250, v78, v79
	s_waitcnt lgkmcnt(6)
	v_mfma_f32_32x32x16_bf16 v[0:15], v[190:193], v[210:213], v[0:15]
	ds_read_b64_tr_b16 v[210:211], v177 offset:0x2200
	ds_read_b64_tr_b16 v[212:213], v177 offset:0x2a00
	v_mov_b32_e32 v251, v250
	s_nop 1
	v_permlane32_swap_b32_e32 v250, v251
	v_max_f32_e32 v250, v250, v251
	v_sub_f32_e32 v251, v250, v186
	v_cmp_ge_f32_e32 vcc, s33, v251
	v_max_f32_e32 v251, v186, v186
	v_max_f32_e32 v250, v251, v250
	s_waitcnt lgkmcnt(6)
	v_mfma_f32_32x32x16_bf16 v[0:15], v[194:197], v[214:217], v[0:15]
	ds_read_b64_tr_b16 v[214:215], v177 offset:0x3200
	ds_read_b64_tr_b16 v[216:217], v177 offset:0x3a00
	v_sub_f32_e32 v251, v186, v250
	v_mul_f32_e32 v251, 0x3e38aa3b, v251
	v_exp_f32_e32 v251, v251
	s_cmp_eq_u64 vcc, exec
	s_cselect_b64 s[6:7], -1, 0
	v_cndmask_b32_e64 v186, v250, v186, s[6:7]
	v_mul_f32_e32 v254, 0xbe38aa3b, v186
	s_waitcnt lgkmcnt(6)
	v_mfma_f32_32x32x16_bf16 v[48:63], v[128:131], v[202:205], v[48:63]
	ds_read_b64_tr_b16 v[202:203], v177 offset:0x400
	ds_read_b64_tr_b16 v[204:205], v177 offset:0xc00
	v_fmamk_f32 v80, v80, 0x3e38aa3b, v254
	v_fmamk_f32 v81, v81, 0x3e38aa3b, v254
	v_fmamk_f32 v64, v64, 0x3e38aa3b, v254
	v_fmamk_f32 v65, v65, 0x3e38aa3b, v254
	v_exp_f32_e32 v234, v80
	v_exp_f32_e32 v235, v81
	v_fmamk_f32 v82, v82, 0x3e38aa3b, v254
	v_fmamk_f32 v83, v83, 0x3e38aa3b, v254
	s_waitcnt lgkmcnt(6)
	v_mfma_f32_32x32x16_bf16 v[48:63], v[198:201], v[206:209], v[48:63]
	ds_read_b64_tr_b16 v[206:207], v177 offset:0x1400
	ds_read_b64_tr_b16 v[208:209], v177 offset:0x1c00
	v_exp_f32_e32 v218, v64
	v_exp_f32_e32 v219, v65
	v_fmamk_f32 v66, v66, 0x3e38aa3b, v254
	v_fmamk_f32 v67, v67, 0x3e38aa3b, v254
	v_exp_f32_e32 v236, v82
	s_waitcnt lgkmcnt(6)
	v_mfma_f32_32x32x16_bf16 v[48:63], v[190:193], v[210:213], v[48:63]
	ds_read_b64_tr_b16 v[210:211], v177 offset:0x2400
	ds_read_b64_tr_b16 v[212:213], v177 offset:0x2c00
	v_exp_f32_e32 v237, v83
	v_fmamk_f32 v84, v84, 0x3e38aa3b, v254
	v_fmamk_f32 v85, v85, 0x3e38aa3b, v254
	v_exp_f32_e32 v220, v66
	v_exp_f32_e32 v221, v67
	s_waitcnt lgkmcnt(6)
	v_mfma_f32_32x32x16_bf16 v[48:63], v[194:197], v[214:217], v[48:63]
	ds_read_b64_tr_b16 v[214:215], v177 offset:0x3400
	ds_read_b64_tr_b16 v[216:217], v177 offset:0x3c00
	v_fmamk_f32 v68, v68, 0x3e38aa3b, v254
	v_fmamk_f32 v69, v69, 0x3e38aa3b, v254
	v_exp_f32_e32 v238, v84
	v_exp_f32_e32 v239, v85
	v_fmamk_f32 v86, v86, 0x3e38aa3b, v254
	v_fmamk_f32 v87, v87, 0x3e38aa3b, v254
	s_waitcnt lgkmcnt(6)
	v_mfma_f32_32x32x16_bf16 v[32:47], v[128:131], v[202:205], v[32:47]
	ds_read_b64_tr_b16 v[202:203], v177 offset:0x600
	ds_read_b64_tr_b16 v[204:205], v177 offset:0xe00
	v_exp_f32_e32 v222, v68
	v_exp_f32_e32 v223, v69
	v_fmamk_f32 v70, v70, 0x3e38aa3b, v254
	v_fmamk_f32 v71, v71, 0x3e38aa3b, v254
	v_exp_f32_e32 v240, v86
	s_waitcnt lgkmcnt(6)
	v_mfma_f32_32x32x16_bf16 v[32:47], v[198:201], v[206:209], v[32:47]
	ds_read_b64_tr_b16 v[206:207], v177 offset:0x1600
	ds_read_b64_tr_b16 v[208:209], v177 offset:0x1e00
	v_exp_f32_e32 v241, v87
	v_fmamk_f32 v88, v88, 0x3e38aa3b, v254
	v_fmamk_f32 v89, v89, 0x3e38aa3b, v254
	v_exp_f32_e32 v224, v70
	v_exp_f32_e32 v225, v71
	s_waitcnt lgkmcnt(6)
	v_mfma_f32_32x32x16_bf16 v[32:47], v[190:193], v[210:213], v[32:47]
	ds_read_b64_tr_b16 v[210:211], v177 offset:0x2600
	ds_read_b64_tr_b16 v[212:213], v177 offset:0x2e00
	v_fmamk_f32 v72, v72, 0x3e38aa3b, v254
	v_fmamk_f32 v73, v73, 0x3e38aa3b, v254
	v_exp_f32_e32 v242, v88
	v_exp_f32_e32 v243, v89
	v_fmamk_f32 v90, v90, 0x3e38aa3b, v254
	v_fmamk_f32 v91, v91, 0x3e38aa3b, v254
	s_waitcnt lgkmcnt(6)
	v_mfma_f32_32x32x16_bf16 v[32:47], v[194:197], v[214:217], v[32:47]
	ds_read_b64_tr_b16 v[214:215], v177 offset:0x3600
	ds_read_b64_tr_b16 v[216:217], v177 offset:0x3e00
	v_exp_f32_e32 v226, v72
	v_exp_f32_e32 v227, v73
	v_fmamk_f32 v74, v74, 0x3e38aa3b, v254
	v_fmamk_f32 v75, v75, 0x3e38aa3b, v254
	v_exp_f32_e32 v244, v90
	s_waitcnt lgkmcnt(6)
	v_mfma_f32_32x32x16_bf16 v[16:31], v[128:131], v[202:205], v[16:31]
	v_exp_f32_e32 v245, v91
	v_fmamk_f32 v92, v92, 0x3e38aa3b, v254
	v_fmamk_f32 v93, v93, 0x3e38aa3b, v254
	v_exp_f32_e32 v228, v74
	v_exp_f32_e32 v229, v75
	s_waitcnt lgkmcnt(4)
	v_mfma_f32_32x32x16_bf16 v[16:31], v[198:201], v[206:209], v[16:31]
	v_fmamk_f32 v76, v76, 0x3e38aa3b, v254
	v_fmamk_f32 v77, v77, 0x3e38aa3b, v254
	v_exp_f32_e32 v246, v92
	v_exp_f32_e32 v247, v93
	v_fmamk_f32 v94, v94, 0x3e38aa3b, v254
	v_fmamk_f32 v95, v95, 0x3e38aa3b, v254
	s_waitcnt lgkmcnt(2)
	v_mfma_f32_32x32x16_bf16 v[16:31], v[190:193], v[210:213], v[16:31]
	v_exp_f32_e32 v230, v76
	v_exp_f32_e32 v231, v77
	v_fmamk_f32 v78, v78, 0x3e38aa3b, v254
	v_fmamk_f32 v79, v79, 0x3e38aa3b, v254
	v_exp_f32_e32 v252, v94
	s_waitcnt lgkmcnt(0)
	v_mfma_f32_32x32x16_bf16 v[16:31], v[194:197], v[214:217], v[16:31]
	v_exp_f32_e32 v253, v95
	s_nop 0
	v_exp_f32_e32 v232, v78
	v_exp_f32_e32 v233, v79
	s_barrier
	s_waitcnt vmcnt(0)
	v_cndmask_b32_e64 v202, v251, 1.0, s[6:7]
	v_cmp_gt_f32_e32 vcc, 1.0, v202
	ds_write_b128 v134, v[112:115]
	ds_write_b128 v145, v[124:127]
	ds_write_b128 v175, v[116:119] offset:32768
	ds_write_b128 v180, v[120:123] offset:32768
	s_cbranch_vccz .LBB0_219
	s_and_saveexec_b64 s[60:61], s[4:5]
	ds_write_b32 v176, v202 offset:128
	s_or_b64 exec, exec, s[60:61]
	s_waitcnt lgkmcnt(0)
	v_add_u32_e32 v124, v174, v144
	ds_read_b128 v[112:115], v124 offset:224
	ds_read_b128 v[116:119], v124 offset:192
	ds_read_b128 v[120:123], v124 offset:160
	ds_read_b128 v[124:127], v124 offset:128
	s_waitcnt lgkmcnt(3)
	v_pk_mul_f32 v[12:13], v[12:13], v[112:113]
	s_waitcnt lgkmcnt(2)
	v_pk_mul_f32 v[8:9], v[8:9], v[116:117]
	s_waitcnt lgkmcnt(1)
	v_pk_mul_f32 v[4:5], v[4:5], v[120:121]
	v_pk_mul_f32 v[14:15], v[14:15], v[114:115]
	v_pk_mul_f32 v[10:11], v[10:11], v[118:119]
	v_pk_mul_f32 v[6:7], v[6:7], v[122:123]
	s_waitcnt lgkmcnt(0)
	v_pk_mul_f32 v[2:3], v[2:3], v[126:127]
	v_pk_mul_f32 v[0:1], v[0:1], v[124:125]
	v_pk_mul_f32 v[60:61], v[60:61], v[112:113]
	v_pk_mul_f32 v[56:57], v[56:57], v[116:117]
	v_pk_mul_f32 v[52:53], v[52:53], v[120:121]
	v_pk_mul_f32 v[62:63], v[62:63], v[114:115]
	v_pk_mul_f32 v[58:59], v[58:59], v[118:119]
	v_pk_mul_f32 v[54:55], v[54:55], v[122:123]
	v_pk_mul_f32 v[50:51], v[50:51], v[126:127]
	v_pk_mul_f32 v[48:49], v[48:49], v[124:125]
	v_pk_mul_f32 v[44:45], v[44:45], v[112:113]
	v_pk_mul_f32 v[40:41], v[40:41], v[116:117]
	v_pk_mul_f32 v[36:37], v[36:37], v[120:121]
	v_pk_mul_f32 v[46:47], v[46:47], v[114:115]
	v_pk_mul_f32 v[42:43], v[42:43], v[118:119]
	v_pk_mul_f32 v[38:39], v[38:39], v[122:123]
	v_pk_mul_f32 v[34:35], v[34:35], v[126:127]
	v_pk_mul_f32 v[32:33], v[32:33], v[124:125]
	v_pk_mul_f32 v[28:29], v[28:29], v[112:113]
	v_pk_mul_f32 v[24:25], v[24:25], v[116:117]
	v_pk_mul_f32 v[20:21], v[20:21], v[120:121]
	v_pk_mul_f32 v[30:31], v[30:31], v[114:115]
	v_pk_mul_f32 v[26:27], v[26:27], v[118:119]
	v_pk_mul_f32 v[22:23], v[22:23], v[122:123]
	v_pk_mul_f32 v[18:19], v[18:19], v[126:127]
	v_pk_mul_f32 v[16:17], v[16:17], v[124:125]
.LBB0_219:
	s_waitcnt lgkmcnt(0)
	s_barrier
	ds_read_b128 v[64:67], v181 offset:32768
	ds_read_b128 v[68:71], v181 offset:40960
	v_add_f32_e32 v201, v235, v234
	v_add_f32_e32 v201, v236, v201
	s_waitcnt lgkmcnt(1)
	v_mfma_f32_32x32x16_bf16 v[80:95], v[64:67], v[108:111], 0
	v_add_f32_e32 v201, v237, v201
	v_add_f32_e32 v201, v238, v201
	ds_read_b128 v[204:207], v182 offset:32768
	ds_read_b128 v[208:211], v182 offset:40960
	v_add_f32_e32 v201, v239, v201
	v_add_f32_e32 v201, v240, v201
	v_add_f32_e32 v201, v241, v201
	v_add_f32_e32 v201, v242, v201
	s_waitcnt lgkmcnt(2)
	v_mfma_f32_32x32x16_bf16 v[64:79], v[68:71], v[108:111], 0
	v_add_f32_e32 v201, v243, v201
	v_add_f32_e32 v201, v244, v201
	v_add_f32_e32 v201, v245, v201
	v_add_f32_e32 v201, v246, v201
	v_add_f32_e32 v201, v247, v201
	v_add_f32_e32 v201, v252, v201
	v_add_f32_e32 v201, v253, v201
	s_waitcnt lgkmcnt(1)
	v_mfma_f32_32x32x16_bf16 v[80:95], v[204:207], v[104:107], v[80:95]
	v_add_f32_e32 v201, v218, v201
	v_add_f32_e32 v201, v219, v201
	v_add_f32_e32 v201, v220, v201
	v_add_f32_e32 v201, v221, v201
	v_add_f32_e32 v201, v222, v201
	v_add_f32_e32 v201, v223, v201
	v_add_f32_e32 v201, v224, v201
	s_waitcnt lgkmcnt(0)
	v_mfma_f32_32x32x16_bf16 v[64:79], v[208:211], v[104:107], v[64:79]
	ds_read_b128 v[204:207], v183 offset:32768
	ds_read_b128 v[208:211], v183 offset:40960
	v_add_f32_e32 v201, v225, v201
	v_add_f32_e32 v201, v226, v201
	v_add_f32_e32 v201, v227, v201
	v_add_f32_e32 v201, v228, v201
	v_add_f32_e32 v201, v229, v201
	v_add_f32_e32 v201, v230, v201
	s_waitcnt lgkmcnt(1)
	v_mfma_f32_32x32x16_bf16 v[80:95], v[204:207], v[100:103], v[80:95]
	v_add_f32_e32 v201, v231, v201
	v_add_f32_e32 v201, v232, v201
	v_add_f32_e32 v203, v233, v201
	s_waitcnt lgkmcnt(0)
	v_mfma_f32_32x32x16_bf16 v[64:79], v[208:211], v[100:103], v[64:79]
	ds_read_b128 v[204:207], v184 offset:32768
	ds_read_b128 v[208:211], v184 offset:40960
	v_cvt_pk_bf16_f32 v128, v234, v235
	v_cvt_pk_bf16_f32 v129, v236, v237
	v_cvt_pk_bf16_f32 v130, v238, v239
	v_cvt_pk_bf16_f32 v131, v240, v241
	v_cvt_pk_bf16_f32 v198, v242, v243
	v_cvt_pk_bf16_f32 v199, v244, v245
	s_waitcnt lgkmcnt(1)
	v_mfma_f32_32x32x16_bf16 v[80:95], v[204:207], v[96:99], v[80:95]
	v_mov_b32_e32 v204, v203
	s_nop 1
	v_permlane32_swap_b32_e32 v203, v204
	v_permlane32_swap_b32_e32 v128, v130
	v_permlane32_swap_b32_e32 v129, v131
	s_waitcnt lgkmcnt(0)
	v_mfma_f32_32x32x16_bf16 v[64:79], v[208:211], v[96:99], v[64:79]
	v_add_co_u32_e32 v116, vcc, s78, v152
	s_nop 1
	v_addc_co_u32_e32 v117, vcc, 0, v153, vcc
	v_add_co_u32_e32 v120, vcc, s78, v150
	s_nop 1
	v_addc_co_u32_e32 v121, vcc, 0, v151, vcc
	ds_read_b64_tr_b16 v[150:151], v179 offset:0
	ds_read_b64_tr_b16 v[152:153], v179 offset:0x800
	ds_read_b64_tr_b16 v[206:207], v179 offset:0x1000
	ds_read_b64_tr_b16 v[208:209], v179 offset:0x1800
	ds_read_b64_tr_b16 v[210:211], v179 offset:0x2000
	ds_read_b64_tr_b16 v[212:213], v179 offset:0x2800
	ds_read_b64_tr_b16 v[214:215], v179 offset:0x3000
	ds_read_b64_tr_b16 v[216:217], v179 offset:0x3800
	v_cvt_pk_bf16_f32 v200, v246, v247
	v_cvt_pk_bf16_f32 v201, v252, v253
	v_cvt_pk_bf16_f32 v190, v218, v219
	v_cvt_pk_bf16_f32 v191, v220, v221
	v_cvt_pk_bf16_f32 v192, v222, v223
	v_cvt_pk_bf16_f32 v193, v224, v225
	v_cvt_pk_bf16_f32 v194, v226, v227
	v_cvt_pk_bf16_f32 v195, v228, v229
	v_cvt_pk_bf16_f32 v196, v230, v231
	v_cvt_pk_bf16_f32 v197, v232, v233
	s_nop 0
	v_permlane32_swap_b32_e32 v198, v200
	v_permlane32_swap_b32_e32 v199, v201
	v_permlane32_swap_b32_e32 v190, v192
	v_permlane32_swap_b32_e32 v191, v193
	v_permlane32_swap_b32_e32 v194, v196
	v_permlane32_swap_b32_e32 v195, v197
	global_load_dwordx4 v[112:115], v[116:117], off offset:1024
	s_nop 0
	global_load_dwordx4 v[116:119], v[116:117], off
	s_nop 0
	global_load_dwordx4 v[124:127], v[120:121], off offset:1024
	s_nop 0
	global_load_dwordx4 v[120:123], v[120:121], off
	s_waitcnt lgkmcnt(6)
	v_mfma_f32_32x32x16_bf16 v[0:15], v[128:131], v[150:153], v[0:15]
	ds_read_b64_tr_b16 v[150:151], v179 offset:0x200
	ds_read_b64_tr_b16 v[152:153], v179 offset:0xa00
	v_max_f32_e32 v250, v80, v81
	v_max3_f32 v250, v250, v82, v83
	v_max3_f32 v250, v250, v84, v85
	v_max3_f32 v250, v250, v86, v87
	v_max3_f32 v250, v250, v88, v89
	v_max3_f32 v250, v250, v90, v91
	v_max3_f32 v250, v250, v92, v93
	s_waitcnt lgkmcnt(6)
	v_mfma_f32_32x32x16_bf16 v[0:15], v[198:201], v[206:209], v[0:15]
	ds_read_b64_tr_b16 v[206:207], v179 offset:0x1200
	ds_read_b64_tr_b16 v[208:209], v179 offset:0x1a00
	v_max3_f32 v250, v250, v94, v95
	v_max3_f32 v250, v250, v64, v65
	v_max3_f32 v250, v250, v66, v67
	v_max3_f32 v250, v250, v68, v69
	v_max3_f32 v250, v250, v70, v71
	v_max3_f32 v250, v250, v72, v73
	v_max3_f32 v250, v250, v74, v75
	v_max3_f32 v250, v250, v76, v77
	v_max3_f32 v250, v250, v78, v79
	s_waitcnt lgkmcnt(6)
	v_mfma_f32_32x32x16_bf16 v[0:15], v[190:193], v[210:213], v[0:15]
	ds_read_b64_tr_b16 v[210:211], v179 offset:0x2200
	ds_read_b64_tr_b16 v[212:213], v179 offset:0x2a00
	v_mov_b32_e32 v251, v250
	s_nop 1
	v_permlane32_swap_b32_e32 v250, v251
	v_max_f32_e32 v250, v250, v251
	v_sub_f32_e32 v251, v250, v186
	v_cmp_ge_f32_e32 vcc, s33, v251
	v_max_f32_e32 v251, v186, v186
	v_max_f32_e32 v251, v251, v250
	s_waitcnt lgkmcnt(6)
	v_mfma_f32_32x32x16_bf16 v[0:15], v[194:197], v[214:217], v[0:15]
	ds_read_b64_tr_b16 v[214:215], v179 offset:0x3200
	ds_read_b64_tr_b16 v[216:217], v179 offset:0x3a00
	v_sub_f32_e32 v250, v186, v251
	v_mul_f32_e32 v250, 0x3e38aa3b, v250
	v_exp_f32_e32 v250, v250
	s_cmp_eq_u64 vcc, exec
	s_cselect_b64 s[6:7], -1, 0
	v_cndmask_b32_e64 v186, v251, v186, s[6:7]
	v_mul_f32_e32 v254, 0xbe38aa3b, v186
	s_waitcnt lgkmcnt(6)
	v_mfma_f32_32x32x16_bf16 v[48:63], v[128:131], v[150:153], v[48:63]
	ds_read_b64_tr_b16 v[150:151], v179 offset:0x400
	ds_read_b64_tr_b16 v[152:153], v179 offset:0xc00
	v_fmamk_f32 v80, v80, 0x3e38aa3b, v254
	v_fmamk_f32 v81, v81, 0x3e38aa3b, v254
	v_fmamk_f32 v64, v64, 0x3e38aa3b, v254
	v_fmamk_f32 v65, v65, 0x3e38aa3b, v254
	v_exp_f32_e32 v234, v80
	v_exp_f32_e32 v235, v81
	v_fmamk_f32 v82, v82, 0x3e38aa3b, v254
	v_fmamk_f32 v83, v83, 0x3e38aa3b, v254
	s_waitcnt lgkmcnt(6)
	v_mfma_f32_32x32x16_bf16 v[48:63], v[198:201], v[206:209], v[48:63]
	ds_read_b64_tr_b16 v[206:207], v179 offset:0x1400
	ds_read_b64_tr_b16 v[208:209], v179 offset:0x1c00
	v_exp_f32_e32 v218, v64
	v_exp_f32_e32 v219, v65
	v_fmamk_f32 v66, v66, 0x3e38aa3b, v254
	v_fmamk_f32 v67, v67, 0x3e38aa3b, v254
	v_exp_f32_e32 v236, v82
	s_waitcnt lgkmcnt(6)
	v_mfma_f32_32x32x16_bf16 v[48:63], v[190:193], v[210:213], v[48:63]
	ds_read_b64_tr_b16 v[210:211], v179 offset:0x2400
	ds_read_b64_tr_b16 v[212:213], v179 offset:0x2c00
	v_exp_f32_e32 v237, v83
	v_fmamk_f32 v84, v84, 0x3e38aa3b, v254
	v_fmamk_f32 v85, v85, 0x3e38aa3b, v254
	v_exp_f32_e32 v220, v66
	v_exp_f32_e32 v221, v67
	s_waitcnt lgkmcnt(6)
	v_mfma_f32_32x32x16_bf16 v[48:63], v[194:197], v[214:217], v[48:63]
	ds_read_b64_tr_b16 v[214:215], v179 offset:0x3400
	ds_read_b64_tr_b16 v[216:217], v179 offset:0x3c00
	v_fmamk_f32 v68, v68, 0x3e38aa3b, v254
	v_fmamk_f32 v69, v69, 0x3e38aa3b, v254
	v_exp_f32_e32 v238, v84
	v_exp_f32_e32 v239, v85
	v_fmamk_f32 v86, v86, 0x3e38aa3b, v254
	v_fmamk_f32 v87, v87, 0x3e38aa3b, v254
	s_waitcnt lgkmcnt(6)
	v_mfma_f32_32x32x16_bf16 v[32:47], v[128:131], v[150:153], v[32:47]
	ds_read_b64_tr_b16 v[150:151], v179 offset:0x600
	ds_read_b64_tr_b16 v[152:153], v179 offset:0xe00
	v_exp_f32_e32 v222, v68
	v_exp_f32_e32 v223, v69
	v_fmamk_f32 v70, v70, 0x3e38aa3b, v254
	v_fmamk_f32 v71, v71, 0x3e38aa3b, v254
	v_exp_f32_e32 v240, v86
	s_waitcnt lgkmcnt(6)
	v_mfma_f32_32x32x16_bf16 v[32:47], v[198:201], v[206:209], v[32:47]
	ds_read_b64_tr_b16 v[206:207], v179 offset:0x1600
	ds_read_b64_tr_b16 v[208:209], v179 offset:0x1e00
	v_exp_f32_e32 v241, v87
	v_fmamk_f32 v88, v88, 0x3e38aa3b, v254
	v_fmamk_f32 v89, v89, 0x3e38aa3b, v254
	v_exp_f32_e32 v224, v70
	v_exp_f32_e32 v225, v71
	s_waitcnt lgkmcnt(6)
	v_mfma_f32_32x32x16_bf16 v[32:47], v[190:193], v[210:213], v[32:47]
	ds_read_b64_tr_b16 v[210:211], v179 offset:0x2600
	ds_read_b64_tr_b16 v[212:213], v179 offset:0x2e00
	v_fmamk_f32 v72, v72, 0x3e38aa3b, v254
	v_fmamk_f32 v73, v73, 0x3e38aa3b, v254
	v_exp_f32_e32 v242, v88
	v_exp_f32_e32 v243, v89
	v_fmamk_f32 v90, v90, 0x3e38aa3b, v254
	v_fmamk_f32 v91, v91, 0x3e38aa3b, v254
	s_waitcnt lgkmcnt(6)
	v_mfma_f32_32x32x16_bf16 v[32:47], v[194:197], v[214:217], v[32:47]
	ds_read_b64_tr_b16 v[214:215], v179 offset:0x3600
	ds_read_b64_tr_b16 v[216:217], v179 offset:0x3e00
	v_exp_f32_e32 v226, v72
	v_exp_f32_e32 v227, v73
	v_fmamk_f32 v74, v74, 0x3e38aa3b, v254
	v_fmamk_f32 v75, v75, 0x3e38aa3b, v254
	v_exp_f32_e32 v244, v90
	s_waitcnt lgkmcnt(6)
	v_mfma_f32_32x32x16_bf16 v[16:31], v[128:131], v[150:153], v[16:31]
	v_exp_f32_e32 v245, v91
	v_fmamk_f32 v92, v92, 0x3e38aa3b, v254
	v_fmamk_f32 v93, v93, 0x3e38aa3b, v254
	v_exp_f32_e32 v228, v74
	v_exp_f32_e32 v229, v75
	s_waitcnt lgkmcnt(4)
	v_mfma_f32_32x32x16_bf16 v[16:31], v[198:201], v[206:209], v[16:31]
	v_fmamk_f32 v76, v76, 0x3e38aa3b, v254
	v_fmamk_f32 v77, v77, 0x3e38aa3b, v254
	v_exp_f32_e32 v246, v92
	v_exp_f32_e32 v247, v93
	v_fmamk_f32 v94, v94, 0x3e38aa3b, v254
	v_fmamk_f32 v95, v95, 0x3e38aa3b, v254
	s_waitcnt lgkmcnt(2)
	v_mfma_f32_32x32x16_bf16 v[16:31], v[190:193], v[210:213], v[16:31]
	v_exp_f32_e32 v230, v76
	v_exp_f32_e32 v231, v77
	v_fmamk_f32 v78, v78, 0x3e38aa3b, v254
	v_fmamk_f32 v79, v79, 0x3e38aa3b, v254
	v_exp_f32_e32 v252, v94
	s_waitcnt lgkmcnt(0)
	v_mfma_f32_32x32x16_bf16 v[16:31], v[194:197], v[214:217], v[16:31]
	v_exp_f32_e32 v253, v95
	s_nop 0
	v_exp_f32_e32 v232, v78
	v_exp_f32_e32 v233, v79
	s_barrier
	s_waitcnt vmcnt(0)
	v_cndmask_b32_e64 v128, v250, 1.0, s[6:7]
	v_cmp_gt_f32_e32 vcc, 1.0, v128
	ds_write_b128 v134, v[112:115] offset:16384
	ds_write_b128 v145, v[124:127] offset:16384
	ds_write_b128 v175, v[116:119] offset:49152
	ds_write_b128 v180, v[120:123] offset:49152
	s_cbranch_vccz .LBB0_223
	s_and_saveexec_b64 s[60:61], s[4:5]
	ds_write_b32 v176, v128 offset:128
	s_or_b64 exec, exec, s[60:61]
	s_waitcnt lgkmcnt(0)
	v_add_u32_e32 v124, v174, v144
	ds_read_b128 v[112:115], v124 offset:224
	ds_read_b128 v[116:119], v124 offset:192
	ds_read_b128 v[120:123], v124 offset:160
	ds_read_b128 v[124:127], v124 offset:128
	s_waitcnt lgkmcnt(3)
	v_pk_mul_f32 v[12:13], v[12:13], v[112:113]
	s_waitcnt lgkmcnt(2)
	v_pk_mul_f32 v[8:9], v[8:9], v[116:117]
	s_waitcnt lgkmcnt(1)
	v_pk_mul_f32 v[4:5], v[4:5], v[120:121]
	v_pk_mul_f32 v[14:15], v[14:15], v[114:115]
	v_pk_mul_f32 v[10:11], v[10:11], v[118:119]
	v_pk_mul_f32 v[6:7], v[6:7], v[122:123]
	s_waitcnt lgkmcnt(0)
	v_pk_mul_f32 v[2:3], v[2:3], v[126:127]
	v_pk_mul_f32 v[0:1], v[0:1], v[124:125]
	v_pk_mul_f32 v[60:61], v[60:61], v[112:113]
	v_pk_mul_f32 v[56:57], v[56:57], v[116:117]
	v_pk_mul_f32 v[52:53], v[52:53], v[120:121]
	v_pk_mul_f32 v[62:63], v[62:63], v[114:115]
	v_pk_mul_f32 v[58:59], v[58:59], v[118:119]
	v_pk_mul_f32 v[54:55], v[54:55], v[122:123]
	v_pk_mul_f32 v[50:51], v[50:51], v[126:127]
	v_pk_mul_f32 v[48:49], v[48:49], v[124:125]
	v_pk_mul_f32 v[44:45], v[44:45], v[112:113]
	v_pk_mul_f32 v[40:41], v[40:41], v[116:117]
	v_pk_mul_f32 v[36:37], v[36:37], v[120:121]
	v_pk_mul_f32 v[46:47], v[46:47], v[114:115]
	v_pk_mul_f32 v[42:43], v[42:43], v[118:119]
	v_pk_mul_f32 v[38:39], v[38:39], v[122:123]
	v_pk_mul_f32 v[34:35], v[34:35], v[126:127]
	v_pk_mul_f32 v[32:33], v[32:33], v[124:125]
	v_pk_mul_f32 v[28:29], v[28:29], v[112:113]
	v_pk_mul_f32 v[24:25], v[24:25], v[116:117]
	v_pk_mul_f32 v[20:21], v[20:21], v[120:121]
	v_pk_mul_f32 v[30:31], v[30:31], v[114:115]
	v_pk_mul_f32 v[26:27], v[26:27], v[118:119]
	v_pk_mul_f32 v[22:23], v[22:23], v[122:123]
	v_pk_mul_f32 v[18:19], v[18:19], v[126:127]
	v_pk_mul_f32 v[16:17], v[16:17], v[124:125]
